# Work-queue pop moved to wave 1 (a softmax-component-1 wave with no outstanding output stores), so the atomic round trip overlaps the component-0 epilogue
# speedup vs baseline: 1.0138x; 1.0060x over previous
; #define LAS __attribute__((address_space(3)))
; #define LAS __attribute__((address_space(3)))
; __global__ void __launch_bounds__(512, 2) hybrid_fwd(Args a) {
;     ...
;                 for (;; ++it) {
;                     const ldsp slot = lds + LDS_PHASE + 16 + (it & 1) * 4;
;                     if (tid == 0) *(LAS unsigned*)slot = __hip_atomic_fetch_add(ctr + xq * 64, 1u, __ATOMIC_RELAXED, __HIP_MEMORY_SCOPE_AGENT);
;                     __syncthreads();
;                     const int idx = (int)*(LAS unsigned*)slot;
.LBB0_403:
	s_lshl_b32 s0, s6, 2
	s_mov_b32 s87, s6
	s_and_b32 s6, s0, 4
	v_cmp_eq_u32_e64 s[100:101], 64, v136
	s_and_saveexec_b64 s[0:1], s[100:101]
	s_cbranch_execz .LBB0_407
	s_mov_b64 s[42:43], exec
	v_mbcnt_lo_u32_b32 v0, s42, 0
	v_mbcnt_hi_u32_b32 v0, s43, v0
	v_cmp_eq_u32_e32 vcc, 0, v0
	s_and_saveexec_b64 s[28:29], vcc
	s_cbranch_execz .LBB0_406
	s_bcnt1_i32_b64 s8, s[42:43]
	v_mov_b32_e32 v1, s8
	global_atomic_add v1, v157, v1, s[76:77] sc0
